# v30 + gate/up GEMM: accumulators no longer zeroed by 128 v_mov per tile; the first MFMA touching each accumulator in the peeled first K iteration takes C=0 inline (exact)
# speedup vs baseline: 1.0116x; 1.0072x over previous
.LBB0_145:
	s_ashr_i32 s17, s16, 31
	s_lshl_b64 s[18:19], s[16:17], 19
	s_add_u32 s18, s36, s18
	s_addc_u32 s19, s37, s19
	s_and_b64 s[20:21], s[2:3], exec
	s_cselect_b32 s17, s19, s25
	s_cselect_b32 s50, s18, s24
	s_ashr_i32 s15, s14, 31
	s_lshl_b64 s[20:21], s[14:15], 19
	s_add_u32 s20, s34, s20
	s_addc_u32 s21, s35, s21
	s_and_b64 s[28:29], s[2:3], exec
	s_cselect_b32 s15, s21, s27
	s_cselect_b32 s51, s20, s26
	s_add_u32 s24, s24, 0x40080
	s_addc_u32 s25, s25, 0
	s_add_u32 s52, s26, 0x100
	s_addc_u32 s53, s27, 0
	s_mov_b32 s54, -2
	s_add_u32 s26, s24, 0xfffc0080
	s_addc_u32 s27, s25, -1
	s_add_i32 s55, 0, 0x10000
	s_cmp_eq_u32 s54, 12
	s_cselect_b32 s29, s17, s27
	s_cselect_b32 s28, s50, s26
	v_add_u32_e32 v140, s55, v143
	s_cselect_b32 s27, s15, s53
	s_cselect_b32 s26, s51, s52
	s_add_i32 s60, 0, 0x14000
	ds_read_b128 v[150:153], v140
	ds_read_b128 v[154:157], v140 offset:1024
	ds_read_b128 v[158:161], v140 offset:2048
	ds_read_b128 v[162:165], v140 offset:3072
	v_add_u32_e32 v140, s60, v143
	ds_read_b128 v[166:169], v140
	ds_read_b128 v[170:173], v140 offset:1024
	ds_read_b128 v[174:177], v140 offset:2048
	ds_read_b128 v[178:181], v140 offset:3072
	v_lshl_add_u64 v[140:141], s[24:25], 0, v[136:137]
	s_add_i32 m0, s40, 0xc000
	ds_read_b128 v[182:185], v148
	ds_read_b128 v[186:189], v148 offset:1024
	ds_read_b128 v[190:193], v148 offset:2048
	ds_read_b128 v[202:205], v148 offset:3072
	ds_read_b128 v[206:209], v148 offset:4096
	ds_read_b128 v[210:213], v148 offset:5120
	ds_read_b128 v[214:217], v148 offset:6144
	ds_read_b128 v[218:221], v148 offset:7168
	global_load_lds_dwordx4 v[140:141], off
	v_lshl_add_u64 v[140:141], s[24:25], 0, v[138:139]
	s_add_i32 m0, s40, 0xe000
	s_nop 0
	global_load_lds_dwordx4 v[140:141], off
	s_waitcnt lgkmcnt(0)
	s_barrier
	s_setprio 1
	s_waitcnt lgkmcnt(0)
	v_mfma_f32_16x16x32_bf16 v[126:129], v[150:153], v[182:185], 0
	v_mfma_f32_16x16x32_bf16 v[118:121], v[158:161], v[182:185], 0
	v_mfma_f32_16x16x32_bf16 v[110:113], v[150:153], v[190:193], 0
	v_mfma_f32_16x16x32_bf16 v[102:105], v[158:161], v[190:193], 0
	v_mfma_f32_16x16x32_bf16 v[92:95], v[150:153], v[206:209], 0
	v_mfma_f32_16x16x32_bf16 v[84:87], v[158:161], v[206:209], 0
	v_mfma_f32_16x16x32_bf16 v[76:79], v[150:153], v[214:217], 0
	v_mfma_f32_16x16x32_bf16 v[68:71], v[158:161], v[214:217], 0
	v_mfma_f32_16x16x32_bf16 v[126:129], v[154:157], v[186:189], v[126:129]
	v_mfma_f32_16x16x32_bf16 v[118:121], v[162:165], v[186:189], v[118:121]
	v_mfma_f32_16x16x32_bf16 v[110:113], v[154:157], v[202:205], v[110:113]
	v_mfma_f32_16x16x32_bf16 v[102:105], v[162:165], v[202:205], v[102:105]
	v_mfma_f32_16x16x32_bf16 v[92:95], v[154:157], v[210:213], v[92:95]
	v_mfma_f32_16x16x32_bf16 v[84:87], v[162:165], v[210:213], v[84:87]
	v_mfma_f32_16x16x32_bf16 v[76:79], v[154:157], v[218:221], v[76:79]
	v_mfma_f32_16x16x32_bf16 v[68:71], v[162:165], v[218:221], v[68:71]
	s_setprio 0
	s_setprio 1
	v_mfma_f32_16x16x32_bf16 v[122:125], v[166:169], v[182:185], 0
	v_mfma_f32_16x16x32_bf16 v[114:117], v[174:177], v[182:185], 0
	v_mfma_f32_16x16x32_bf16 v[106:109], v[166:169], v[190:193], 0
	v_mfma_f32_16x16x32_bf16 v[98:101], v[174:177], v[190:193], 0
	v_mfma_f32_16x16x32_bf16 v[88:91], v[166:169], v[206:209], 0
	v_mfma_f32_16x16x32_bf16 v[80:83], v[174:177], v[206:209], 0
	v_mfma_f32_16x16x32_bf16 v[72:75], v[166:169], v[214:217], 0
	v_mfma_f32_16x16x32_bf16 v[64:67], v[174:177], v[214:217], 0
	v_mfma_f32_16x16x32_bf16 v[122:125], v[170:173], v[186:189], v[122:125]
	v_mfma_f32_16x16x32_bf16 v[114:117], v[178:181], v[186:189], v[114:117]
	v_mfma_f32_16x16x32_bf16 v[106:109], v[170:173], v[202:205], v[106:109]
	v_mfma_f32_16x16x32_bf16 v[98:101], v[178:181], v[202:205], v[98:101]
	v_mfma_f32_16x16x32_bf16 v[88:91], v[170:173], v[210:213], v[88:91]
	v_mfma_f32_16x16x32_bf16 v[80:83], v[178:181], v[210:213], v[80:83]
	v_mfma_f32_16x16x32_bf16 v[72:75], v[170:173], v[218:221], v[72:75]
	v_mfma_f32_16x16x32_bf16 v[64:67], v[178:181], v[218:221], v[64:67]
	s_setprio 0
	s_barrier
	s_add_i32 s55, s55, s39
	v_lshl_add_u64 v[140:141], s[26:27], 0, v[96:97]
	s_mov_b32 m0, s55
	ds_read_b128 v[182:185], v148 offset:16384
	ds_read_b128 v[186:189], v148 offset:17408
	ds_read_b128 v[190:193], v148 offset:18432
	ds_read_b128 v[202:205], v148 offset:19456
	ds_read_b128 v[206:209], v148 offset:20480
	ds_read_b128 v[210:213], v148 offset:21504
	ds_read_b128 v[214:217], v148 offset:22528
	ds_read_b128 v[218:221], v148 offset:23552
	global_load_lds_dwordx4 v[140:141], off
	s_add_i32 m0, s55, 0x2000
	s_add_u32 s56, s26, 0x40000
	v_lshl_add_u64 v[194:195], s[26:27], 0, v[130:131]
	s_addc_u32 s57, s27, 0
	s_add_i32 s55, s60, s39
	global_load_lds_dwordx4 v[194:195], off
	v_lshl_add_u64 v[196:197], s[56:57], 0, v[96:97]
	s_mov_b32 m0, s55
	v_lshl_add_u64 v[198:199], s[28:29], 0, v[132:133]
	global_load_lds_dwordx4 v[196:197], off
	v_lshl_add_u64 v[196:197], s[56:57], 0, v[130:131]
	s_add_i32 m0, s55, 0x2000
	s_nop 0
	global_load_lds_dwordx4 v[196:197], off
	v_lshl_add_u64 v[196:197], s[28:29], 0, v[134:135]
	s_mov_b32 m0, s40
	s_nop 0
	global_load_lds_dwordx4 v[196:197], off
	s_mov_b32 m0, s41
	s_nop 0
	global_load_lds_dwordx4 v[198:199], off
	s_waitcnt lgkmcnt(0)
	s_barrier
	s_setprio 1
	s_waitcnt lgkmcnt(0)
	v_mfma_f32_16x16x32_bf16 v[60:63], v[150:153], v[182:185], 0
	v_mfma_f32_16x16x32_bf16 v[52:55], v[158:161], v[182:185], 0
	v_mfma_f32_16x16x32_bf16 v[44:47], v[150:153], v[190:193], 0
	v_mfma_f32_16x16x32_bf16 v[36:39], v[158:161], v[190:193], 0
	v_mfma_f32_16x16x32_bf16 v[28:31], v[150:153], v[206:209], 0
	v_mfma_f32_16x16x32_bf16 v[20:23], v[158:161], v[206:209], 0
	v_mfma_f32_16x16x32_bf16 v[12:15], v[150:153], v[214:217], 0
	v_mfma_f32_16x16x32_bf16 v[4:7], v[158:161], v[214:217], 0
	v_mfma_f32_16x16x32_bf16 v[60:63], v[154:157], v[186:189], v[60:63]
	v_mfma_f32_16x16x32_bf16 v[52:55], v[162:165], v[186:189], v[52:55]
	v_mfma_f32_16x16x32_bf16 v[44:47], v[154:157], v[202:205], v[44:47]
	v_mfma_f32_16x16x32_bf16 v[36:39], v[162:165], v[202:205], v[36:39]
	v_mfma_f32_16x16x32_bf16 v[28:31], v[154:157], v[210:213], v[28:31]
	v_mfma_f32_16x16x32_bf16 v[20:23], v[162:165], v[210:213], v[20:23]
	v_mfma_f32_16x16x32_bf16 v[12:15], v[154:157], v[218:221], v[12:15]
	v_mfma_f32_16x16x32_bf16 v[4:7], v[162:165], v[218:221], v[4:7]
	s_setprio 0
	s_setprio 1
	v_mfma_f32_16x16x32_bf16 v[56:59], v[166:169], v[182:185], 0
	v_mfma_f32_16x16x32_bf16 v[48:51], v[174:177], v[182:185], 0
	v_mfma_f32_16x16x32_bf16 v[40:43], v[166:169], v[190:193], 0
	v_mfma_f32_16x16x32_bf16 v[32:35], v[174:177], v[190:193], 0
	v_mfma_f32_16x16x32_bf16 v[24:27], v[166:169], v[206:209], 0
	v_mfma_f32_16x16x32_bf16 v[16:19], v[174:177], v[206:209], 0
	v_mfma_f32_16x16x32_bf16 v[8:11], v[166:169], v[214:217], 0
	v_mfma_f32_16x16x32_bf16 v[0:3], v[174:177], v[214:217], 0
	v_mfma_f32_16x16x32_bf16 v[56:59], v[170:173], v[186:189], v[56:59]
	v_mfma_f32_16x16x32_bf16 v[48:51], v[178:181], v[186:189], v[48:51]
	v_mfma_f32_16x16x32_bf16 v[40:43], v[170:173], v[202:205], v[40:43]
	v_mfma_f32_16x16x32_bf16 v[32:35], v[178:181], v[202:205], v[32:35]
	v_mfma_f32_16x16x32_bf16 v[24:27], v[170:173], v[210:213], v[24:27]
	v_mfma_f32_16x16x32_bf16 v[16:19], v[178:181], v[210:213], v[16:19]
	v_mfma_f32_16x16x32_bf16 v[8:11], v[170:173], v[218:221], v[8:11]
	v_mfma_f32_16x16x32_bf16 v[0:3], v[178:181], v[218:221], v[0:3]
	s_setprio 0
	s_barrier
	s_add_i32 s55, 0, 0x18000
	v_add_u32_e32 v149, s55, v143
	s_add_i32 s56, 0, 0x1c000
	ds_read_b128 v[150:153], v149
	ds_read_b128 v[154:157], v149 offset:1024
	ds_read_b128 v[158:161], v149 offset:2048
	ds_read_b128 v[162:165], v149 offset:3072
	v_add_u32_e32 v149, s56, v143
	ds_read_b128 v[166:169], v149
	ds_read_b128 v[170:173], v149 offset:1024
	ds_read_b128 v[174:177], v149 offset:2048
	ds_read_b128 v[178:181], v149 offset:3072
	s_add_u32 s28, s28, 0x40000
	s_addc_u32 s29, s29, 0
	s_mov_b32 m0, s42
	v_lshl_add_u64 v[200:201], s[28:29], 0, v[134:135]
	ds_read_b128 v[182:185], v148 offset:32768
	ds_read_b128 v[186:189], v148 offset:33792
	ds_read_b128 v[190:193], v148 offset:34816
	ds_read_b128 v[202:205], v148 offset:35840
	ds_read_b128 v[206:209], v148 offset:36864
	ds_read_b128 v[210:213], v148 offset:37888
	ds_read_b128 v[214:217], v148 offset:38912
	ds_read_b128 v[218:221], v148 offset:39936
	global_load_lds_dwordx4 v[200:201], off
	v_lshl_add_u64 v[200:201], s[28:29], 0, v[132:133]
	s_mov_b32 m0, s43
	s_nop 0
	global_load_lds_dwordx4 v[200:201], off
	s_waitcnt vmcnt(8)
	s_waitcnt lgkmcnt(0)
	s_barrier
	s_setprio 1
	s_waitcnt lgkmcnt(0)
	v_mfma_f32_16x16x32_bf16 v[126:129], v[150:153], v[182:185], v[126:129]
	v_mfma_f32_16x16x32_bf16 v[118:121], v[158:161], v[182:185], v[118:121]
	v_mfma_f32_16x16x32_bf16 v[110:113], v[150:153], v[190:193], v[110:113]
	v_mfma_f32_16x16x32_bf16 v[102:105], v[158:161], v[190:193], v[102:105]
	v_mfma_f32_16x16x32_bf16 v[92:95], v[150:153], v[206:209], v[92:95]
	v_mfma_f32_16x16x32_bf16 v[84:87], v[158:161], v[206:209], v[84:87]
	v_mfma_f32_16x16x32_bf16 v[76:79], v[150:153], v[214:217], v[76:79]
	v_mfma_f32_16x16x32_bf16 v[68:71], v[158:161], v[214:217], v[68:71]
	v_mfma_f32_16x16x32_bf16 v[126:129], v[154:157], v[186:189], v[126:129]
	v_mfma_f32_16x16x32_bf16 v[118:121], v[162:165], v[186:189], v[118:121]
	v_mfma_f32_16x16x32_bf16 v[110:113], v[154:157], v[202:205], v[110:113]
	v_mfma_f32_16x16x32_bf16 v[102:105], v[162:165], v[202:205], v[102:105]
	v_mfma_f32_16x16x32_bf16 v[92:95], v[154:157], v[210:213], v[92:95]
	v_mfma_f32_16x16x32_bf16 v[84:87], v[162:165], v[210:213], v[84:87]
	v_mfma_f32_16x16x32_bf16 v[76:79], v[154:157], v[218:221], v[76:79]
	v_mfma_f32_16x16x32_bf16 v[68:71], v[162:165], v[218:221], v[68:71]
	s_setprio 0
	s_setprio 1
	v_mfma_f32_16x16x32_bf16 v[122:125], v[166:169], v[182:185], v[122:125]
	v_mfma_f32_16x16x32_bf16 v[114:117], v[174:177], v[182:185], v[114:117]
	v_mfma_f32_16x16x32_bf16 v[106:109], v[166:169], v[190:193], v[106:109]
	v_mfma_f32_16x16x32_bf16 v[98:101], v[174:177], v[190:193], v[98:101]
	v_mfma_f32_16x16x32_bf16 v[88:91], v[166:169], v[206:209], v[88:91]
	v_mfma_f32_16x16x32_bf16 v[80:83], v[174:177], v[206:209], v[80:83]
	v_mfma_f32_16x16x32_bf16 v[72:75], v[166:169], v[214:217], v[72:75]
	v_mfma_f32_16x16x32_bf16 v[64:67], v[174:177], v[214:217], v[64:67]
	v_mfma_f32_16x16x32_bf16 v[122:125], v[170:173], v[186:189], v[122:125]
	v_mfma_f32_16x16x32_bf16 v[114:117], v[178:181], v[186:189], v[114:117]
	v_mfma_f32_16x16x32_bf16 v[106:109], v[170:173], v[202:205], v[106:109]
	v_mfma_f32_16x16x32_bf16 v[98:101], v[178:181], v[202:205], v[98:101]
	v_mfma_f32_16x16x32_bf16 v[88:91], v[170:173], v[210:213], v[88:91]
	v_mfma_f32_16x16x32_bf16 v[80:83], v[178:181], v[210:213], v[80:83]
	v_mfma_f32_16x16x32_bf16 v[72:75], v[170:173], v[218:221], v[72:75]
	v_mfma_f32_16x16x32_bf16 v[64:67], v[178:181], v[218:221], v[64:67]
	s_setprio 0
	s_barrier
	s_add_i32 s28, s55, s39
	v_lshl_add_u64 v[140:141], v[140:141], 0, s[64:65]
	s_mov_b32 m0, s28
	ds_read_b128 v[182:185], v148 offset:49152
	ds_read_b128 v[186:189], v148 offset:50176
	ds_read_b128 v[190:193], v148 offset:51200
	ds_read_b128 v[202:205], v148 offset:52224
	ds_read_b128 v[206:209], v148 offset:53248
	ds_read_b128 v[210:213], v148 offset:54272
	ds_read_b128 v[214:217], v148 offset:55296
	ds_read_b128 v[218:221], v148 offset:56320
	global_load_lds_dwordx4 v[140:141], off
	s_add_i32 m0, s28, 0x2000
	s_add_u32 s26, s26, 0x40080
	v_lshl_add_u64 v[140:141], v[194:195], 0, s[64:65]
	s_addc_u32 s27, s27, 0
	s_add_i32 s28, s56, s39
	global_load_lds_dwordx4 v[140:141], off
	v_lshl_add_u64 v[140:141], s[26:27], 0, v[96:97]
	s_mov_b32 m0, s28
	s_nop 0
	global_load_lds_dwordx4 v[140:141], off
	v_lshl_add_u64 v[140:141], s[26:27], 0, v[130:131]
	s_add_i32 m0, s28, 0x2000
	s_nop 0
	global_load_lds_dwordx4 v[140:141], off
	v_lshl_add_u64 v[140:141], v[196:197], 0, s[64:65]
	s_mov_b32 m0, s44
	s_nop 0
	global_load_lds_dwordx4 v[140:141], off
	v_lshl_add_u64 v[140:141], v[198:199], 0, s[64:65]
	s_mov_b32 m0, s45
	s_nop 0
	global_load_lds_dwordx4 v[140:141], off
	s_waitcnt vmcnt(8)
	s_waitcnt lgkmcnt(0)
	s_barrier
	s_setprio 1
	s_waitcnt lgkmcnt(0)
	v_mfma_f32_16x16x32_bf16 v[60:63], v[150:153], v[182:185], v[60:63]
	v_mfma_f32_16x16x32_bf16 v[52:55], v[158:161], v[182:185], v[52:55]
	v_mfma_f32_16x16x32_bf16 v[44:47], v[150:153], v[190:193], v[44:47]
	v_mfma_f32_16x16x32_bf16 v[36:39], v[158:161], v[190:193], v[36:39]
	v_mfma_f32_16x16x32_bf16 v[28:31], v[150:153], v[206:209], v[28:31]
	v_mfma_f32_16x16x32_bf16 v[20:23], v[158:161], v[206:209], v[20:23]
	v_mfma_f32_16x16x32_bf16 v[12:15], v[150:153], v[214:217], v[12:15]
	v_mfma_f32_16x16x32_bf16 v[4:7], v[158:161], v[214:217], v[4:7]
	v_mfma_f32_16x16x32_bf16 v[60:63], v[154:157], v[186:189], v[60:63]
	v_mfma_f32_16x16x32_bf16 v[52:55], v[162:165], v[186:189], v[52:55]
	v_mfma_f32_16x16x32_bf16 v[44:47], v[154:157], v[202:205], v[44:47]
	v_mfma_f32_16x16x32_bf16 v[36:39], v[162:165], v[202:205], v[36:39]
	v_mfma_f32_16x16x32_bf16 v[28:31], v[154:157], v[210:213], v[28:31]
	v_mfma_f32_16x16x32_bf16 v[20:23], v[162:165], v[210:213], v[20:23]
	v_mfma_f32_16x16x32_bf16 v[12:15], v[154:157], v[218:221], v[12:15]
	v_mfma_f32_16x16x32_bf16 v[4:7], v[162:165], v[218:221], v[4:7]
	s_setprio 0
	s_setprio 1
	v_mfma_f32_16x16x32_bf16 v[56:59], v[166:169], v[182:185], v[56:59]
	v_mfma_f32_16x16x32_bf16 v[48:51], v[174:177], v[182:185], v[48:51]
	v_mfma_f32_16x16x32_bf16 v[40:43], v[166:169], v[190:193], v[40:43]
	v_mfma_f32_16x16x32_bf16 v[32:35], v[174:177], v[190:193], v[32:35]
	v_mfma_f32_16x16x32_bf16 v[24:27], v[166:169], v[206:209], v[24:27]
	v_mfma_f32_16x16x32_bf16 v[16:19], v[174:177], v[206:209], v[16:19]
	v_mfma_f32_16x16x32_bf16 v[8:11], v[166:169], v[214:217], v[8:11]
	v_mfma_f32_16x16x32_bf16 v[0:3], v[174:177], v[214:217], v[0:3]
	v_mfma_f32_16x16x32_bf16 v[56:59], v[170:173], v[186:189], v[56:59]
	v_mfma_f32_16x16x32_bf16 v[48:51], v[178:181], v[186:189], v[48:51]
	v_mfma_f32_16x16x32_bf16 v[40:43], v[170:173], v[202:205], v[40:43]
	v_mfma_f32_16x16x32_bf16 v[32:35], v[178:181], v[202:205], v[32:35]
	v_mfma_f32_16x16x32_bf16 v[24:27], v[170:173], v[210:213], v[24:27]
	v_mfma_f32_16x16x32_bf16 v[16:19], v[178:181], v[210:213], v[16:19]
	v_mfma_f32_16x16x32_bf16 v[8:11], v[170:173], v[218:221], v[8:11]
	v_mfma_f32_16x16x32_bf16 v[0:3], v[178:181], v[218:221], v[0:3]
	s_setprio 0
	s_barrier
	s_add_i32 s54, s54, 2
	s_add_u32 s24, s24, 0x100
	s_addc_u32 s25, s25, 0
	s_add_u32 s52, s52, 0x100
	s_addc_u32 s53, s53, 0
	s_cmp_gt_u32 s54, 13
	s_cbranch_scc1 .Lgu_kdone
